# v33 plus q/k head-norm loop with four adjacent heads per iteration
# baseline (speedup 1.0000x reference)
; __device__ __forceinline__ void ew_phase(const Params& p, int l) {
;     ...
;         const int t = tid & 15; const long grp = ((long)blockIdx.x * NTHREADS + tid) >> 4, ngrp = (long)gridDim.x * NTHREADS / 16;
;         const float2* rope = (const float2*)(ws + WS_ROPE);
;         const int base = ((t & 8) ? 64 : 0) + 4 * (t & 7), fi = 4 * (t & 7);
;         bf16_t* KC = (bf16_t*)(ws + WS_KC);
; #pragma unroll 2
;         for (long it = grp; it < (long)ROWS * 20; it += ngrp) { const int row = (int)(it / 20), head = (int)(it % 20);
.LBB0_244:
	s_andn2_b64 vcc, exec, s[0:1]
	s_cbranch_vccnz .LBB0_282
	s_cmp_gt_i32 s46, 5
	s_mov_b64 s[0:1], -1
	s_cbranch_scc0 .LBB0_266
	v_mov_b32_e32 v0, v190
	v_readlane_b32 s0, v246, 21
	v_readlane_b32 s1, v246, 22
	v_ashrrev_i32_e32 v1, 31, v0
	s_mov_b32 s21, s86
	v_lshl_add_u64 v[114:115], s[0:1], 0, v[0:1]
	v_ashrrev_i64 v[2:3], 4, v[114:115]
	s_mov_b64 s[0:1], 0x29400
	s_mov_b32 s20, s85
	v_cmp_gt_i64_e32 vcc, s[0:1], v[2:3]
	s_and_saveexec_b64 s[4:5], vcc
	s_cbranch_execz .LBB0_253
	v_lshlrev_b32_e32 v5, 2, v0
	v_and_b32_e32 v5, 28, v5
	v_and_b32_e32 v4, 8, v0
	v_and_b32_e32 v6, 64, v191
	v_lshlrev_b32_e32 v96, 3, v5
	v_cmp_eq_u32_e32 vcc, 0, v4
	v_lshl_or_b32 v4, v4, 3, v5
	v_add_u32_e32 v8, 64, v6
	v_lshl_add_u64 v[6:7], s[54:55], 0, v[96:97]
	s_mov_b64 s[0:1], 0x1c8f0000
	v_xor_b32_e32 v5, 8, v191
	v_lshl_add_u64 v[6:7], v[6:7], 0, s[0:1]
	v_cmp_lt_i32_e64 s[0:1], v5, v8
	v_xor_b32_e32 v9, 4, v191
	v_xor_b32_e32 v10, 2, v191
	v_cndmask_b32_e64 v5, v191, v5, s[0:1]
	v_cmp_lt_i32_e64 s[0:1], v9, v8
	v_lshlrev_b32_e32 v5, 2, v5
	s_mov_b64 s[14:15], 0
	v_cndmask_b32_e64 v9, v191, v9, s[0:1]
	v_cmp_lt_i32_e64 s[0:1], v10, v8
	v_lshlrev_b32_e32 v9, 2, v9
	s_nop 0
	v_cndmask_b32_e64 v10, v191, v10, s[0:1]
	v_lshlrev_b32_e32 v26, 2, v10
	v_xor_b32_e32 v10, 1, v191
	v_cmp_lt_i32_e64 s[0:1], v10, v8
	s_nop 1
	v_cndmask_b32_e64 v8, v191, v10, s[0:1]
	v_readlane_b32 s0, v246, 23
	v_lshlrev_b32_e32 v27, 2, v8
	v_lshlrev_b64 v[2:3], 2, v[2:3]
	v_lshlrev_b32_e32 v8, 7, v2
	s_lshl_b32 s18, s0, 9
	v_readlane_b32 s1, v246, 24
	s_branch .LBB0_249

; __device__ __forceinline__ unsigned cvtpk(float lo, float hi) { unsigned r; asm volatile("v_cvt_pk_bf16_f32 %0, %1, %2" : "=v"(r) : "v"(lo), "v"(hi)); return r; }
; __device__ __forceinline__ float bflo(unsigned w) { return __uint_as_float(w << 16); }
; __device__ __forceinline__ float bfhi(unsigned w) { return __uint_as_float(w & 0xffff0000u); }
; __device__ __forceinline__ void ew_phase(const Params& p, int l) {
;     ...
;             const u32x2 wa = *(const u32x2*)src_, wb = *(const u32x2*)(src_ + 32);
;             const f32x4 ga = *(const f32x4*)gn, gb = *(const f32x4*)(gn + 32);
;             float a[4] = {bflo(wa.x), bfhi(wa.x), bflo(wa.y), bfhi(wa.y)}, b[4] = {bflo(wb.x), bfhi(wb.x), bflo(wb.y), bfhi(wb.y)};
;             float ss = 0.f;
; #pragma unroll
;             for (int q = 0; q < 4; ++q) ss += a[q] * a[q] + b[q] * b[q];
; #pragma unroll
;             for (int o = 8; o >= 1; o >>= 1) ss += __shfl_xor(ss, o);
;             const float rstd = rsqrtf(ss * (1.0f / 128.0f) + EPS);
; #pragma unroll
;             for (int q = 0; q < 4; ++q) { a[q] = a[q] * rstd * ga[q]; b[q] = b[q] * rstd * gb[q]; }
;             if (row >= CTX) { const int tk = row - CTX, pos = (t & 8) ? (tk & 63) : (tk >> 6);
;                 const f32x4 r01 = *(const f32x4*)(rope + pos * 32 + fi), r23 = *(const f32x4*)(rope + pos * 32 + fi + 2);
;                 const float cs[4] = {r01[0], r01[2], r23[0], r23[2]}, sn[4] = {r01[1], r01[3], r23[1], r23[3]};
; #pragma unroll
;                 for (int q = 0; q < 4; ++q) { const float x0 = a[q], x1 = b[q]; a[q] = x0 * cs[q] - x1 * sn[q]; b[q] = x0 * sn[q] + x1 * cs[q]; } }
;             u32x2 oa, ob; oa.x = cvtpk(a[0], a[1]); oa.y = cvtpk(a[2], a[3]); ob.x = cvtpk(b[0], b[1]); ob.y = cvtpk(b[2], b[3]);
;             *(u32x2*)dst_ = oa; *(u32x2*)(dst_ + 32) = ob;
.Lqk_bjoin:
	s_or_b64 exec, exec, s[16:17]
	v_cvt_pk_bf16_f32 v212, v220, v223
	v_cvt_pk_bf16_f32 v213, v214, v217
	v_cvt_pk_bf16_f32 v214, v218, v219
	v_cvt_pk_bf16_f32 v215, v224, v225
	s_mov_b32 s0, 0x800000
	v_lshl_add_u64 v[130:131], v[210:211], 0, v[96:97]
	v_lshlrev_b32_e32 v140, 16, v138
	v_and_b32_e32 v141, 0xffff0000, v134
	v_lshlrev_b32_e32 v136, 16, v134
	v_and_b32_e32 v137, 0xffff0000, v138
	v_pk_mul_f32 v[144:145], v[140:141], v[140:141]
	v_lshlrev_b32_e32 v158, 16, v135
	v_and_b32_e32 v159, 0xffff0000, v139
	v_pk_fma_f32 v[144:145], v[136:137], v[136:137], v[144:145]
	v_lshlrev_b32_e32 v134, 16, v139
	v_and_b32_e32 v135, 0xffff0000, v135
	v_pk_mul_f32 v[138:139], v[158:159], v[158:159]
	v_add_f32_e32 v133, v144, v145
	v_pk_fma_f32 v[138:139], v[134:135], v[134:135], v[138:139]
	v_mov_b32_e32 v142, v136
	v_add_f32_e32 v133, v138, v133
	v_add_f32_e32 v133, v139, v133
	ds_bpermute_b32 v138, v5, v133
	v_mov_b32_e32 v143, v141
	v_mov_b32_e32 v156, v152
	v_mov_b32_e32 v157, v149
	v_mov_b32_e32 v149, v153
	s_waitcnt lgkmcnt(0)
	v_add_f32_e32 v133, v133, v138
	ds_bpermute_b32 v138, v9, v133
	v_mov_b32_e32 v160, v158
	v_mov_b32_e32 v161, v135
	s_waitcnt lgkmcnt(0)
	v_add_f32_e32 v133, v133, v138
	ds_bpermute_b32 v138, v26, v133
	s_waitcnt lgkmcnt(0)
	v_add_f32_e32 v133, v133, v138
	ds_bpermute_b32 v138, v27, v133
	s_waitcnt lgkmcnt(0)
	v_add_f32_e32 v133, v133, v138
	v_fmamk_f32 v133, v133, 0x3c000000, v193
	v_cmp_gt_f32_e64 s[0:1], s0, v133
	v_mul_f32_e32 v138, 0x4b800000, v133
	s_nop 0
	v_cndmask_b32_e64 v133, v133, v138, s[0:1]
	v_rsq_f32_e32 v133, v133
	s_nop 0
	v_mul_f32_e32 v138, 0x45800000, v133
	v_cndmask_b32_e64 v144, v133, v138, s[0:1]
	v_pk_mul_f32 v[138:139], v[144:145], v[140:141] op_sel_hi:[0,1]
	v_pk_mul_f32 v[136:137], v[144:145], v[136:137] op_sel_hi:[0,1]
	v_pk_mul_f32 v[162:163], v[144:145], v[142:143] op_sel_hi:[0,1]
	v_pk_mul_f32 v[142:143], v[156:157], v[136:137]
	v_pk_mul_f32 v[140:141], v[148:149], v[138:139]
	v_pk_mul_f32 v[134:135], v[144:145], v[134:135] op_sel_hi:[0,1]
	v_pk_mul_f32 v[136:137], v[144:145], v[158:159] op_sel_hi:[0,1]
	v_pk_mul_f32 v[144:145], v[144:145], v[160:161] op_sel_hi:[0,1]
	v_mov_b32_e32 v148, v154
	v_mov_b32_e32 v149, v151
	v_mov_b32_e32 v151, v155
	s_mov_b64 s[0:1], 0x13ff
	v_pk_mul_f32 v[138:139], v[152:153], v[162:163]
	v_pk_mul_f32 v[136:137], v[148:149], v[136:137]
	v_pk_mul_f32 v[134:135], v[150:151], v[134:135]
	v_pk_mul_f32 v[144:145], v[154:155], v[144:145]
	v_cmp_lt_i64_e64 s[0:1], s[0:1], v[2:3]
	s_and_saveexec_b64 s[16:17], s[0:1]
	s_cbranch_execz .Lqk_cjoin
	v_mov_b32_e32 v156, v142
	v_mov_b32_e32 v157, v141
	v_mov_b32_e32 v138, v140
	v_mov_b32_e32 v139, v143
	v_mov_b32_e32 v144, v134
	v_mov_b32_e32 v145, v137
	v_mov_b32_e32 v158, v165
	v_mov_b32_e32 v159, v167
	v_mov_b32_e32 v132, v164
	v_mov_b32_e32 v133, v166
	v_pk_mul_f32 v[156:157], v[156:157], v[158:159]
	s_nop 0
	v_pk_fma_f32 v[132:133], v[138:139], v[132:133], v[156:157] neg_lo:[0,0,1] neg_hi:[0,0,1]
	v_mov_b32_e32 v138, v164
	v_mov_b32_e32 v139, v167
	v_pk_mul_f32 v[138:139], v[142:143], v[138:139]
	v_mov_b32_e32 v142, v165
	v_mov_b32_e32 v143, v166
	v_pk_fma_f32 v[138:139], v[140:141], v[142:143], v[138:139]
	v_mov_b32_e32 v142, v136
	v_mov_b32_e32 v143, v135
	v_mov_b32_e32 v164, v169
	v_mov_b32_e32 v165, v171
	v_mov_b32_e32 v140, v168
	v_mov_b32_e32 v141, v170
	v_pk_mul_f32 v[142:143], v[142:143], v[164:165]
	s_nop 0
	v_pk_fma_f32 v[164:165], v[144:145], v[140:141], v[142:143] neg_lo:[0,0,1] neg_hi:[0,0,1]
	v_mov_b32_e32 v141, v171
	v_pk_mul_f32 v[136:137], v[136:137], v[140:141]
	v_mov_b32_e32 v140, v169
	v_mov_b32_e32 v141, v170
	v_pk_fma_f32 v[144:145], v[134:135], v[140:141], v[136:137]
	v_mov_b32_e32 v140, v132
	v_mov_b32_e32 v143, v133
	v_mov_b32_e32 v134, v164
	v_mov_b32_e32 v137, v165
; __device__ __forceinline__ unsigned cvtpk(float lo, float hi) { unsigned r; asm volatile("v_cvt_pk_bf16_f32 %0, %1, %2" : "=v"(r) : "v"(lo), "v"(hi)); return r; }
; __device__ __forceinline__ float bflo(unsigned w) { return __uint_as_float(w << 16); }
; __device__ __forceinline__ float bfhi(unsigned w) { return __uint_as_float(w & 0xffff0000u); }
; __device__ __forceinline__ void ew_phase(const Params& p, int l) {
;     ...
;             const u32x2 wa = *(const u32x2*)src_, wb = *(const u32x2*)(src_ + 32);
;             const f32x4 ga = *(const f32x4*)gn, gb = *(const f32x4*)(gn + 32);
;             float a[4] = {bflo(wa.x), bfhi(wa.x), bflo(wa.y), bfhi(wa.y)}, b[4] = {bflo(wb.x), bfhi(wb.x), bflo(wb.y), bfhi(wb.y)};
;             float ss = 0.f;
; #pragma unroll
;             for (int q = 0; q < 4; ++q) ss += a[q] * a[q] + b[q] * b[q];
; #pragma unroll
;             for (int o = 8; o >= 1; o >>= 1) ss += __shfl_xor(ss, o);
;             const float rstd = rsqrtf(ss * (1.0f / 128.0f) + EPS);
; #pragma unroll
;             for (int q = 0; q < 4; ++q) { a[q] = a[q] * rstd * ga[q]; b[q] = b[q] * rstd * gb[q]; }
;             if (row >= CTX) { const int tk = row - CTX, pos = (t & 8) ? (tk & 63) : (tk >> 6);
;                 const f32x4 r01 = *(const f32x4*)(rope + pos * 32 + fi), r23 = *(const f32x4*)(rope + pos * 32 + fi + 2);
;                 const float cs[4] = {r01[0], r01[2], r23[0], r23[2]}, sn[4] = {r01[1], r01[3], r23[1], r23[3]};
; #pragma unroll
;                 for (int q = 0; q < 4; ++q) { const float x0 = a[q], x1 = b[q]; a[q] = x0 * cs[q] - x1 * sn[q]; b[q] = x0 * sn[q] + x1 * cs[q]; } }
;             u32x2 oa, ob; oa.x = cvtpk(a[0], a[1]); oa.y = cvtpk(a[2], a[3]); ob.x = cvtpk(b[0], b[1]); ob.y = cvtpk(b[2], b[3]);
;             *(u32x2*)dst_ = oa; *(u32x2*)(dst_ + 32) = ob;
.Lqk_cjoin:
	s_or_b64 exec, exec, s[16:17]
	v_cvt_pk_bf16_f32 v132, v140, v143
	v_cvt_pk_bf16_f32 v133, v134, v137
	v_cvt_pk_bf16_f32 v134, v138, v139
	v_cvt_pk_bf16_f32 v135, v144, v145
	s_mov_b32 s0, 0x800000
	v_lshl_add_u64 v[44:45], v[130:131], 0, v[96:97]
	v_lshlrev_b32_e32 v54, 16, v52
	v_and_b32_e32 v55, 0xffff0000, v48
	v_lshlrev_b32_e32 v50, 16, v48
	v_and_b32_e32 v51, 0xffff0000, v52
	v_pk_mul_f32 v[58:59], v[54:55], v[54:55]
	v_lshlrev_b32_e32 v72, 16, v49
	v_and_b32_e32 v73, 0xffff0000, v53
	v_pk_fma_f32 v[58:59], v[50:51], v[50:51], v[58:59]
	v_lshlrev_b32_e32 v48, 16, v53
	v_and_b32_e32 v49, 0xffff0000, v49
	v_pk_mul_f32 v[52:53], v[72:73], v[72:73]
	v_add_f32_e32 v47, v58, v59
	v_pk_fma_f32 v[52:53], v[48:49], v[48:49], v[52:53]
	v_mov_b32_e32 v56, v50
	v_add_f32_e32 v47, v52, v47
	v_add_f32_e32 v47, v53, v47
	ds_bpermute_b32 v52, v5, v47
	v_mov_b32_e32 v57, v55
	v_mov_b32_e32 v70, v66
	v_mov_b32_e32 v71, v63
	v_mov_b32_e32 v63, v67
	s_waitcnt lgkmcnt(0)
	v_add_f32_e32 v47, v47, v52
	ds_bpermute_b32 v52, v9, v47
	v_mov_b32_e32 v74, v72
	v_mov_b32_e32 v75, v49
	s_waitcnt lgkmcnt(0)
	v_add_f32_e32 v47, v47, v52
	ds_bpermute_b32 v52, v26, v47
	s_waitcnt lgkmcnt(0)
	v_add_f32_e32 v47, v47, v52
	ds_bpermute_b32 v52, v27, v47
	s_waitcnt lgkmcnt(0)
	v_add_f32_e32 v47, v47, v52
	v_fmamk_f32 v47, v47, 0x3c000000, v193
	v_cmp_gt_f32_e64 s[0:1], s0, v47
	v_mul_f32_e32 v52, 0x4b800000, v47
	s_nop 0
	v_cndmask_b32_e64 v47, v47, v52, s[0:1]
	v_rsq_f32_e32 v47, v47
	s_nop 0
	v_mul_f32_e32 v52, 0x45800000, v47
	v_cndmask_b32_e64 v58, v47, v52, s[0:1]
	v_pk_mul_f32 v[52:53], v[58:59], v[54:55] op_sel_hi:[0,1]
	v_pk_mul_f32 v[50:51], v[58:59], v[50:51] op_sel_hi:[0,1]
	v_pk_mul_f32 v[76:77], v[58:59], v[56:57] op_sel_hi:[0,1]
	v_pk_mul_f32 v[56:57], v[70:71], v[50:51]
	v_pk_mul_f32 v[54:55], v[62:63], v[52:53]
	v_pk_mul_f32 v[48:49], v[58:59], v[48:49] op_sel_hi:[0,1]
	v_pk_mul_f32 v[50:51], v[58:59], v[72:73] op_sel_hi:[0,1]
	v_pk_mul_f32 v[58:59], v[58:59], v[74:75] op_sel_hi:[0,1]
	v_mov_b32_e32 v62, v68
	v_mov_b32_e32 v63, v65
	v_mov_b32_e32 v65, v69
	s_mov_b64 s[0:1], 0x13ff
	v_pk_mul_f32 v[52:53], v[66:67], v[76:77]
	v_pk_mul_f32 v[50:51], v[62:63], v[50:51]
	v_pk_mul_f32 v[48:49], v[64:65], v[48:49]
	v_pk_mul_f32 v[58:59], v[68:69], v[58:59]
	v_cmp_lt_i64_e64 s[0:1], s[0:1], v[2:3]
	s_and_saveexec_b64 s[16:17], s[0:1]
	s_cbranch_execz .Lqk_djoin
	v_mov_b32_e32 v70, v56
	v_mov_b32_e32 v71, v55
	v_mov_b32_e32 v52, v54
	v_mov_b32_e32 v53, v57
	v_mov_b32_e32 v58, v48
	v_mov_b32_e32 v59, v51
	v_mov_b32_e32 v72, v79
	v_mov_b32_e32 v73, v81
	v_mov_b32_e32 v46, v78
	v_mov_b32_e32 v47, v80
	v_pk_mul_f32 v[70:71], v[70:71], v[72:73]
	s_nop 0
	v_pk_fma_f32 v[46:47], v[52:53], v[46:47], v[70:71] neg_lo:[0,0,1] neg_hi:[0,0,1]
	v_mov_b32_e32 v52, v78
	v_mov_b32_e32 v53, v81
	v_pk_mul_f32 v[52:53], v[56:57], v[52:53]
	v_mov_b32_e32 v56, v79
	v_mov_b32_e32 v57, v80
	v_pk_fma_f32 v[52:53], v[54:55], v[56:57], v[52:53]
	v_mov_b32_e32 v56, v50
	v_mov_b32_e32 v57, v49
	v_mov_b32_e32 v78, v83
	v_mov_b32_e32 v79, v85
	v_mov_b32_e32 v54, v82
	v_mov_b32_e32 v55, v84
	v_pk_mul_f32 v[56:57], v[56:57], v[78:79]
	s_nop 0
	v_pk_fma_f32 v[78:79], v[58:59], v[54:55], v[56:57] neg_lo:[0,0,1] neg_hi:[0,0,1]
	v_mov_b32_e32 v55, v85
	v_pk_mul_f32 v[50:51], v[50:51], v[54:55]
	v_mov_b32_e32 v54, v83
	v_mov_b32_e32 v55, v84
	v_pk_fma_f32 v[58:59], v[48:49], v[54:55], v[50:51]
	v_mov_b32_e32 v54, v46
	v_mov_b32_e32 v57, v47
	v_mov_b32_e32 v48, v78
	v_mov_b32_e32 v51, v79
.Lqk_djoin:
	s_or_b64 exec, exec, s[16:17]
	v_cvt_pk_bf16_f32 v46, v54, v57
	v_cvt_pk_bf16_f32 v47, v48, v51
	v_cvt_pk_bf16_f32 v48, v52, v53
	v_cvt_pk_bf16_f32 v49, v58, v59
	flat_store_dwordx2 v[10:11], v[12:13]
	flat_store_dwordx2 v[10:11], v[14:15] offset:64
	flat_store_dwordx2 v[210:211], v[212:213]
	flat_store_dwordx2 v[210:211], v[214:215] offset:64
	flat_store_dwordx2 v[130:131], v[132:133]
	flat_store_dwordx2 v[130:131], v[134:135] offset:64
	flat_store_dwordx2 v[44:45], v[46:47]
	flat_store_dwordx2 v[44:45], v[48:49] offset:64
	v_readlane_b32 s0, v246, 23
	v_readlane_b32 s1, v246, 24
	s_nop 0
	s_lshl_b64 s[0:1], s[0:1], 2
	v_add_u32_e32 v8, s18, v8
	v_lshl_add_u64 v[2:3], v[2:3], 0, s[0:1]
	s_mov_b64 s[0:1], 0x293ff
	v_cmp_lt_i64_e64 s[0:1], s[0:1], v[2:3]
	s_or_b64 s[14:15], s[0:1], s[14:15]
	s_andn2_b64 exec, exec, s[14:15]
	s_cbranch_execz .LBB0_253

; __device__ __forceinline__ float bflo(unsigned w) { return __uint_as_float(w << 16); }
; __device__ __forceinline__ float bfhi(unsigned w) { return __uint_as_float(w & 0xffff0000u); }
; __device__ __forceinline__ void ew_phase(const Params& p, int l) {
;     ...
;             const bf16_t* src_ = P + (size_t)row * INC + (head < 16 ? OQ + head * 128 : OKK + (head - 16) * 128) + base;
;             bf16_t* dst_ = (head < 16) ? (P + (size_t)row * INC + OQ + head * 128 + base) : (KC + ((size_t)(head - 16) * ROWS + row) * 128 + base);
;             const float* gn = (head < 16 ? p.in[I_QN] : p.in[I_KN]) + (size_t)l * 128 + base;
;             const u32x2 wa = *(const u32x2*)src_, wb = *(const u32x2*)(src_ + 32);
;             const f32x4 ga = *(const f32x4*)gn, gb = *(const f32x4*)(gn + 32);
;             float a[4] = {bflo(wa.x), bfhi(wa.x), bflo(wa.y), bfhi(wa.y)}, b[4] = {bflo(wb.x), bfhi(wb.x), bflo(wb.y), bfhi(wb.y)};
.LBB0_251:
	s_or_b64 exec, exec, s[16:17]
	v_readlane_b32 s0, v245, 45
	v_lshlrev_b32_e32 v96, 1, v4
	v_readlane_b32 s1, v245, 46
	v_lshl_add_u64 v[14:15], v[14:15], 0, v[96:97]
	s_nop 0
	v_lshl_add_u64 v[16:17], v[18:19], 0, s[0:1]
	v_lshlrev_b32_e32 v18, 2, v4
	v_mov_b32_e32 v19, v97
	v_lshl_add_u64 v[16:17], v[16:17], 0, v[18:19]
	flat_load_dwordx2 v[18:19], v[14:15]
	flat_load_dwordx2 v[218:219], v[14:15] offset:256
	flat_load_dwordx2 v[214:215], v[14:15] offset:320
	flat_load_dwordx2 v[138:139], v[14:15] offset:512
	flat_load_dwordx2 v[134:135], v[14:15] offset:576
	flat_load_dwordx2 v[52:53], v[14:15] offset:768
	flat_load_dwordx2 v[48:49], v[14:15] offset:832
	flat_load_dwordx2 v[14:15], v[14:15] offset:64
	global_load_dwordx4 v[28:31], v[16:17], off
	global_load_dwordx4 v[32:35], v[16:17], off offset:128
	global_load_dwordx4 v[228:231], v[16:17], off
	global_load_dwordx4 v[232:235], v[16:17], off offset:128
	global_load_dwordx4 v[148:151], v[16:17], off
	global_load_dwordx4 v[152:155], v[16:17], off offset:128
	global_load_dwordx4 v[62:65], v[16:17], off
	global_load_dwordx4 v[66:69], v[16:17], off offset:128
	s_mov_b64 s[98:99], 0x13ff
	v_cmp_lt_i64_e64 s[98:99], s[98:99], v[2:3]
	s_and_saveexec_b64 s[100:101], s[98:99]
	v_add_u32_e32 v209, 0xffffff00, v12
	v_and_b32_e32 v208, 63, v12
	v_lshrrev_b32_e32 v209, 6, v209
	v_cndmask_b32_e32 v208, v208, v209, vcc
	v_lshlrev_b32_e32 v208, 5, v208
	v_mov_b32_e32 v209, v97
	v_lshl_add_u64 v[208:209], v[208:209], 3, v[6:7]
	flat_load_dwordx4 v[200:203], v[208:209]
	flat_load_dwordx4 v[204:207], v[208:209] offset:16
	flat_load_dwordx4 v[120:123], v[208:209]
	flat_load_dwordx4 v[124:127], v[208:209] offset:16
	flat_load_dwordx4 v[164:167], v[208:209]
	flat_load_dwordx4 v[168:171], v[208:209] offset:16
	flat_load_dwordx4 v[78:81], v[208:209]
	flat_load_dwordx4 v[82:85], v[208:209] offset:16
	s_mov_b64 exec, s[100:101]
	s_mov_b32 s0, 0x800000
	s_waitcnt vmcnt(0) lgkmcnt(0)
	v_lshlrev_b32_e32 v20, 16, v18
	v_and_b32_e32 v21, 0xffff0000, v14
	v_lshlrev_b32_e32 v16, 16, v14
	v_and_b32_e32 v17, 0xffff0000, v18
	v_pk_mul_f32 v[24:25], v[20:21], v[20:21]
	v_lshlrev_b32_e32 v38, 16, v15
	v_and_b32_e32 v39, 0xffff0000, v19
	v_pk_fma_f32 v[24:25], v[16:17], v[16:17], v[24:25]
	v_lshlrev_b32_e32 v14, 16, v19
	v_and_b32_e32 v15, 0xffff0000, v15
	v_pk_mul_f32 v[18:19], v[38:39], v[38:39]
	v_add_f32_e32 v13, v24, v25
	v_pk_fma_f32 v[18:19], v[14:15], v[14:15], v[18:19]
	v_mov_b32_e32 v22, v16
	v_add_f32_e32 v13, v18, v13
	v_add_f32_e32 v13, v19, v13
	ds_bpermute_b32 v18, v5, v13
	v_mov_b32_e32 v23, v21
	v_mov_b32_e32 v36, v32
	v_mov_b32_e32 v37, v29
	v_mov_b32_e32 v29, v33
	s_waitcnt lgkmcnt(0)
	v_add_f32_e32 v13, v13, v18
	ds_bpermute_b32 v18, v9, v13
	v_mov_b32_e32 v40, v38
	v_mov_b32_e32 v41, v15
	s_waitcnt lgkmcnt(0)
	v_add_f32_e32 v13, v13, v18
	ds_bpermute_b32 v18, v26, v13
	s_waitcnt lgkmcnt(0)
	v_add_f32_e32 v13, v13, v18
	ds_bpermute_b32 v18, v27, v13
	s_waitcnt lgkmcnt(0)
	v_add_f32_e32 v13, v13, v18
	v_fmamk_f32 v13, v13, 0x3c000000, v193
	v_cmp_gt_f32_e64 s[0:1], s0, v13
	v_mul_f32_e32 v18, 0x4b800000, v13
	s_nop 0
	v_cndmask_b32_e64 v13, v13, v18, s[0:1]
	v_rsq_f32_e32 v13, v13
	s_nop 0
	v_mul_f32_e32 v18, 0x45800000, v13
	v_cndmask_b32_e64 v24, v13, v18, s[0:1]
	v_pk_mul_f32 v[18:19], v[24:25], v[20:21] op_sel_hi:[0,1]
	v_pk_mul_f32 v[16:17], v[24:25], v[16:17] op_sel_hi:[0,1]
	v_pk_mul_f32 v[42:43], v[24:25], v[22:23] op_sel_hi:[0,1]
	v_pk_mul_f32 v[22:23], v[36:37], v[16:17]
	v_pk_mul_f32 v[20:21], v[28:29], v[18:19]
	v_pk_mul_f32 v[14:15], v[24:25], v[14:15] op_sel_hi:[0,1]
	v_pk_mul_f32 v[16:17], v[24:25], v[38:39] op_sel_hi:[0,1]
	v_pk_mul_f32 v[24:25], v[24:25], v[40:41] op_sel_hi:[0,1]
	v_mov_b32_e32 v28, v34
	v_mov_b32_e32 v29, v31
	v_mov_b32_e32 v31, v35
	s_mov_b64 s[0:1], 0x13ff
	v_pk_mul_f32 v[18:19], v[32:33], v[42:43]
	v_pk_mul_f32 v[16:17], v[28:29], v[16:17]
	v_pk_mul_f32 v[14:15], v[30:31], v[14:15]
	v_pk_mul_f32 v[24:25], v[34:35], v[24:25]
	v_cmp_lt_i64_e64 s[0:1], s[0:1], v[2:3]
	s_and_saveexec_b64 s[16:17], s[0:1]
	s_cbranch_execz .LBB0_248
	v_mov_b32_e32 v36, v22
	v_mov_b32_e32 v37, v21
	v_mov_b32_e32 v18, v20
	v_mov_b32_e32 v19, v23
	v_mov_b32_e32 v24, v14
	v_mov_b32_e32 v25, v17
	s_waitcnt vmcnt(0) lgkmcnt(0)
	v_mov_b32_e32 v38, v201
	v_mov_b32_e32 v39, v203
	v_mov_b32_e32 v12, v200
	v_mov_b32_e32 v13, v202
	v_pk_mul_f32 v[36:37], v[36:37], v[38:39]
	s_nop 0
	v_pk_fma_f32 v[12:13], v[18:19], v[12:13], v[36:37] neg_lo:[0,0,1] neg_hi:[0,0,1]
	v_mov_b32_e32 v18, v200
	v_mov_b32_e32 v19, v203
	v_pk_mul_f32 v[18:19], v[22:23], v[18:19]
	v_mov_b32_e32 v22, v201
	v_mov_b32_e32 v23, v202
	v_pk_fma_f32 v[18:19], v[20:21], v[22:23], v[18:19]
	v_mov_b32_e32 v22, v16
	v_mov_b32_e32 v23, v15
	v_mov_b32_e32 v200, v205
	v_mov_b32_e32 v201, v207
	v_mov_b32_e32 v20, v204
	v_mov_b32_e32 v21, v206
	v_pk_mul_f32 v[22:23], v[22:23], v[200:201]
	s_nop 0
	v_pk_fma_f32 v[200:201], v[24:25], v[20:21], v[22:23] neg_lo:[0,0,1] neg_hi:[0,0,1]
	v_mov_b32_e32 v21, v207
	v_pk_mul_f32 v[16:17], v[16:17], v[20:21]
	v_mov_b32_e32 v20, v205
	v_mov_b32_e32 v21, v206
	v_pk_fma_f32 v[24:25], v[14:15], v[20:21], v[16:17]
	v_mov_b32_e32 v20, v12
	v_mov_b32_e32 v23, v13
	v_mov_b32_e32 v14, v200
	v_mov_b32_e32 v17, v201
	s_branch .LBB0_248
